# attention A: wave-uniform fast path skipping window masking for tiles fully inside the window
# speedup vs baseline: 1.0121x; 1.0045x over previous
.LBB0_777:
	v_add_u32_e32 v200, 0x101, v191
	v_cmp_lt_u32_e32 vcc, 0xc5, v200
	s_cbranch_vccz .Lmaskfast_1
	v_lshl_add_u64 v[86:87], v[170:171], 0, s[14:15]
	ds_read_b128 v[66:69], v189 offset:9216
	ds_read_b128 v[82:85], v189 offset:13824
	ds_read_b128 v[100:103], v189 offset:9248
	ds_read_b128 v[104:107], v189 offset:13856
	ds_read_b128 v[108:111], v189 offset:9280
	ds_read_b128 v[112:115], v189 offset:9312
	global_load_dwordx4 v[150:153], v[86:87], off
	s_waitcnt lgkmcnt(5)
	v_mfma_f32_32x32x16_bf16 v[66:81], v[66:69], v[130:133], 0
	v_cmp_lt_u32_e32 vcc, s29, v191
	ds_read_b128 v[116:119], v189 offset:13888
	ds_read_b128 v[120:123], v189 offset:13920
	v_cndmask_b32_e32 v98, v176, v34, vcc
	v_add_u32_e32 v34, 32, v191
	v_cmp_lt_u32_e32 vcc, s29, v34
	v_add_u32_e32 v34, 1, v191
	s_nop 0
	v_cndmask_b32_e32 v50, v176, v50, vcc
	v_cmp_lt_u32_e32 vcc, s29, v34
	v_add_u32_e32 v34, 33, v191
	s_waitcnt lgkmcnt(6)
	v_mfma_f32_32x32x16_bf16 v[82:97], v[82:85], v[130:133], 0
	v_cndmask_b32_e32 v99, v176, v35, vcc
	v_cmp_lt_u32_e32 vcc, s29, v34
	v_add_u32_e32 v34, 2, v191
	v_add_u32_e32 v35, 26, v191
	v_cndmask_b32_e32 v51, v176, v51, vcc
	v_cmp_lt_u32_e32 vcc, s29, v34
	v_add_u32_e32 v34, 34, v191
	s_waitcnt lgkmcnt(5)
	v_mfma_f32_32x32x16_bf16 v[66:81], v[100:103], v[134:137], v[66:81]
	v_cndmask_b32_e32 v100, v176, v36, vcc
	v_cmp_lt_u32_e32 vcc, s29, v34
	v_add_u32_e32 v34, 3, v191
	v_add_u32_e32 v36, 27, v191
	v_cndmask_b32_e32 v52, v176, v52, vcc
	v_cmp_lt_u32_e32 vcc, s29, v34
	v_add_u32_e32 v34, 35, v191
	s_waitcnt lgkmcnt(4)
	v_mfma_f32_32x32x16_bf16 v[82:97], v[104:107], v[134:137], v[82:97]
	v_cndmask_b32_e32 v101, v176, v37, vcc
	v_cmp_lt_u32_e32 vcc, s29, v34
	v_add_u32_e32 v34, 8, v191
	s_nop 0
	v_cndmask_b32_e32 v53, v176, v53, vcc
	v_cmp_lt_u32_e32 vcc, s29, v34
	v_add_u32_e32 v34, 40, v191
	s_waitcnt lgkmcnt(3)
	v_mfma_f32_32x32x16_bf16 v[66:81], v[108:111], v[138:141], v[66:81]
	v_cndmask_b32_e32 v102, v176, v38, vcc
	v_cmp_lt_u32_e32 vcc, s29, v34
	v_add_u32_e32 v34, 9, v191
	s_nop 0
	v_cndmask_b32_e32 v54, v176, v54, vcc
	v_cmp_lt_u32_e32 vcc, s29, v34
	v_add_u32_e32 v34, 41, v191
	s_waitcnt lgkmcnt(1)
	v_mfma_f32_32x32x16_bf16 v[82:97], v[116:119], v[138:141], v[82:97]
	v_cndmask_b32_e32 v103, v176, v39, vcc
	v_cmp_lt_u32_e32 vcc, s29, v34
	v_add_u32_e32 v34, 10, v191
	s_nop 0
	v_cndmask_b32_e32 v55, v176, v55, vcc
	v_cmp_lt_u32_e32 vcc, s29, v34
	v_add_u32_e32 v34, 42, v191
	v_mfma_f32_32x32x16_bf16 v[66:81], v[112:115], v[142:145], v[66:81]
	v_cndmask_b32_e32 v104, v176, v40, vcc
	v_cmp_lt_u32_e32 vcc, s29, v34
	v_add_u32_e32 v34, 11, v191
	s_nop 0
	v_cndmask_b32_e32 v56, v176, v56, vcc
	v_cmp_lt_u32_e32 vcc, s29, v34
	v_add_u32_e32 v34, 43, v191
	s_waitcnt lgkmcnt(0)
	v_mfma_f32_32x32x16_bf16 v[82:97], v[120:123], v[142:145], v[82:97]
	v_cndmask_b32_e32 v105, v176, v41, vcc
	v_cmp_lt_u32_e32 vcc, s29, v34
	v_add_u32_e32 v34, 16, v191
	s_nop 0
	v_cndmask_b32_e32 v57, v176, v57, vcc
	v_cmp_lt_u32_e32 vcc, s29, v34
	v_add_u32_e32 v34, 48, v191
	s_nop 0
	v_cndmask_b32_e32 v106, v176, v42, vcc
	v_cmp_lt_u32_e32 vcc, s29, v34
	v_add_u32_e32 v34, 17, v191
	s_nop 0
	v_cndmask_b32_e32 v58, v176, v58, vcc
	v_cmp_lt_u32_e32 vcc, s29, v34
	v_add_u32_e32 v34, 49, v191
	s_nop 0
	v_cndmask_b32_e32 v107, v176, v43, vcc
	v_cmp_lt_u32_e32 vcc, s29, v34
	v_add_u32_e32 v34, 18, v191
	s_nop 0
	v_cndmask_b32_e32 v59, v176, v59, vcc
	v_cmp_lt_u32_e32 vcc, s29, v34
	v_add_u32_e32 v34, 50, v191
	s_nop 0
	v_cndmask_b32_e32 v44, v176, v44, vcc
	v_cmp_lt_u32_e32 vcc, s29, v34
	v_add_u32_e32 v34, 19, v191
	s_nop 0
	v_cndmask_b32_e32 v37, v176, v60, vcc
	v_cmp_lt_u32_e32 vcc, s29, v34
	v_add_u32_e32 v34, 51, v191
	s_nop 0
	v_cndmask_b32_e32 v45, v176, v45, vcc
	v_cmp_lt_u32_e32 vcc, s29, v34
	v_add_u32_e32 v34, 24, v191
	s_nop 0
	v_cndmask_b32_e32 v38, v176, v61, vcc
	v_cmp_lt_u32_e32 vcc, s29, v34
	v_add_u32_e32 v34, 56, v191
	s_nop 0
	v_cndmask_b32_e32 v43, v176, v46, vcc
	v_cmp_lt_u32_e32 vcc, s29, v34
	v_add_u32_e32 v34, 25, v191
	s_nop 0
	v_cndmask_b32_e32 v39, v176, v62, vcc
	v_cmp_lt_u32_e32 vcc, s29, v34
	v_add_u32_e32 v34, 57, v191
	s_nop 0
	v_cndmask_b32_e32 v40, v176, v47, vcc
	v_cmp_lt_u32_e32 vcc, s29, v34
	s_nop 1
	v_cndmask_b32_e32 v34, v176, v63, vcc
	v_cmp_lt_u32_e32 vcc, s29, v35
	v_add_u32_e32 v35, 58, v191
	s_nop 0
	v_cndmask_b32_e32 v41, v176, v48, vcc
	v_cmp_lt_u32_e32 vcc, s29, v35
	s_nop 1
	v_cndmask_b32_e32 v35, v176, v64, vcc
	v_cmp_lt_u32_e32 vcc, s29, v36
	v_add_u32_e32 v36, 59, v191
	s_nop 0
	v_cndmask_b32_e32 v42, v176, v49, vcc
	v_cmp_lt_u32_e32 vcc, s29, v36
	s_nop 1
	v_cndmask_b32_e32 v36, v176, v65, vcc
	s_branch .LBB0_779
.Lmaskfast_1:
	v_lshl_add_u64 v[86:87], v[170:171], 0, s[14:15]
	ds_read_b128 v[66:69], v189 offset:9216
	ds_read_b128 v[82:85], v189 offset:13824
	ds_read_b128 v[100:103], v189 offset:9248
	ds_read_b128 v[104:107], v189 offset:13856
	ds_read_b128 v[108:111], v189 offset:9280
	ds_read_b128 v[112:115], v189 offset:9312
	global_load_dwordx4 v[150:153], v[86:87], off
	s_waitcnt lgkmcnt(5)
	v_mfma_f32_32x32x16_bf16 v[66:81], v[66:69], v[130:133], 0
	ds_read_b128 v[116:119], v189 offset:13888
	ds_read_b128 v[120:123], v189 offset:13920
	v_mov_b32_e32 v98, v34
	s_waitcnt lgkmcnt(6)
	v_mfma_f32_32x32x16_bf16 v[82:97], v[82:85], v[130:133], 0
	v_mov_b32_e32 v99, v35
	s_waitcnt lgkmcnt(5)
	v_mfma_f32_32x32x16_bf16 v[66:81], v[100:103], v[134:137], v[66:81]
	v_mov_b32_e32 v100, v36
	s_waitcnt lgkmcnt(4)
	v_mfma_f32_32x32x16_bf16 v[82:97], v[104:107], v[134:137], v[82:97]
	v_mov_b32_e32 v101, v37
	s_waitcnt lgkmcnt(3)
	v_mfma_f32_32x32x16_bf16 v[66:81], v[108:111], v[138:141], v[66:81]
	v_mov_b32_e32 v102, v38
	s_waitcnt lgkmcnt(1)
	v_mfma_f32_32x32x16_bf16 v[82:97], v[116:119], v[138:141], v[82:97]
	v_mov_b32_e32 v103, v39
	v_mfma_f32_32x32x16_bf16 v[66:81], v[112:115], v[142:145], v[66:81]
	v_mov_b32_e32 v104, v40
	s_waitcnt lgkmcnt(0)
	v_mfma_f32_32x32x16_bf16 v[82:97], v[120:123], v[142:145], v[82:97]
	v_mov_b32_e32 v105, v41
	v_mov_b32_e32 v106, v42
	v_mov_b32_e32 v107, v43
	v_mov_b32_e32 v37, v60
	v_mov_b32_e32 v38, v61
	v_mov_b32_e32 v43, v46
	v_mov_b32_e32 v39, v62
	v_mov_b32_e32 v40, v47
	v_mov_b32_e32 v34, v63
	v_mov_b32_e32 v41, v48
	v_mov_b32_e32 v35, v64
	v_mov_b32_e32 v42, v49
	v_mov_b32_e32 v36, v65

.LBB0_786:
	v_pk_add_f32 v[98:99], v[100:101], v[98:99]
	v_pk_add_f32 v[114:115], v[116:117], v[114:115]
	v_pk_add_f32 v[98:99], v[102:103], v[98:99]
	v_pk_add_f32 v[114:115], v[118:119], v[114:115]
	v_pk_add_f32 v[98:99], v[104:105], v[98:99]
	v_pk_add_f32 v[114:115], v[120:121], v[114:115]
	v_pk_add_f32 v[98:99], v[106:107], v[98:99]
	v_pk_add_f32 v[114:115], v[122:123], v[114:115]
	v_pk_add_f32 v[98:99], v[108:109], v[98:99]
	v_pk_add_f32 v[114:115], v[124:125], v[114:115]
	v_pk_add_f32 v[98:99], v[110:111], v[98:99]
	v_pk_add_f32 v[114:115], v[126:127], v[114:115]
	v_pk_add_f32 v[98:99], v[112:113], v[98:99]
	v_pk_add_f32 v[114:115], v[128:129], v[114:115]
	v_add_f32_e32 v98, v98, v99
	v_add_f32_e32 v99, v114, v115
	v_add_f32_e32 v98, v98, v99
	v_add_f32_e32 v0, v0, v98
	v_add_u32_e32 v200, 0x141, v191
	v_cmp_lt_u32_e32 vcc, 0xc5, v200
	s_cbranch_vccz .Lmaskfast_2
	v_add_u32_e32 v98, 64, v191
	v_cmp_lt_u32_e32 vcc, s29, v98
	s_nop 1
	v_cndmask_b32_e32 v98, v176, v66, vcc
	v_add_u32_e32 v66, 0x60, v191
	v_cmp_lt_u32_e32 vcc, s29, v66
	v_add_u32_e32 v66, 0x41, v191
	s_nop 0
	v_cndmask_b32_e32 v82, v176, v82, vcc
	v_cmp_lt_u32_e32 vcc, s29, v66
	v_add_u32_e32 v66, 0x61, v191
	s_nop 0
	v_cndmask_b32_e32 v99, v176, v67, vcc
	v_cmp_lt_u32_e32 vcc, s29, v66
	v_add_u32_e32 v66, 0x42, v191
	v_add_u32_e32 v67, 0x5a, v191
	v_cndmask_b32_e32 v83, v176, v83, vcc
	v_cmp_lt_u32_e32 vcc, s29, v66
	v_add_u32_e32 v66, 0x62, v191
	s_nop 0
	v_cndmask_b32_e32 v100, v176, v68, vcc
	v_cmp_lt_u32_e32 vcc, s29, v66
	v_add_u32_e32 v66, 0x43, v191
	v_add_u32_e32 v68, 0x5b, v191
	v_cndmask_b32_e32 v84, v176, v84, vcc
	v_cmp_lt_u32_e32 vcc, s29, v66
	v_add_u32_e32 v66, 0x63, v191
	s_nop 0
	v_cndmask_b32_e32 v101, v176, v69, vcc
	v_cmp_lt_u32_e32 vcc, s29, v66
	v_add_u32_e32 v66, 0x48, v191
	s_nop 0
	v_cndmask_b32_e32 v85, v176, v85, vcc
	v_cmp_lt_u32_e32 vcc, s29, v66
	v_add_u32_e32 v66, 0x68, v191
	s_nop 0
	v_cndmask_b32_e32 v102, v176, v70, vcc
	v_cmp_lt_u32_e32 vcc, s29, v66
	v_add_u32_e32 v66, 0x49, v191
	s_nop 0
	v_cndmask_b32_e32 v86, v176, v86, vcc
	v_cmp_lt_u32_e32 vcc, s29, v66
	v_add_u32_e32 v66, 0x69, v191
	s_nop 0
	v_cndmask_b32_e32 v103, v176, v71, vcc
	v_cmp_lt_u32_e32 vcc, s29, v66
	v_add_u32_e32 v66, 0x4a, v191
	s_nop 0
	v_cndmask_b32_e32 v87, v176, v87, vcc
	v_cmp_lt_u32_e32 vcc, s29, v66
	v_add_u32_e32 v66, 0x6a, v191
	s_nop 0
	v_cndmask_b32_e32 v104, v176, v72, vcc
	v_cmp_lt_u32_e32 vcc, s29, v66
	v_add_u32_e32 v66, 0x4b, v191
	s_nop 0
	v_cndmask_b32_e32 v88, v176, v88, vcc
	v_cmp_lt_u32_e32 vcc, s29, v66
	v_add_u32_e32 v66, 0x6b, v191
	s_nop 0
	v_cndmask_b32_e32 v105, v176, v73, vcc
	v_cmp_lt_u32_e32 vcc, s29, v66
	v_add_u32_e32 v66, 0x50, v191
	s_nop 0
	v_cndmask_b32_e32 v89, v176, v89, vcc
	v_cmp_lt_u32_e32 vcc, s29, v66
	v_add_u32_e32 v66, 0x70, v191
	s_nop 0
	v_cndmask_b32_e32 v106, v176, v74, vcc
	v_cmp_lt_u32_e32 vcc, s29, v66
	v_add_u32_e32 v66, 0x51, v191
	s_nop 0
	v_cndmask_b32_e32 v90, v176, v90, vcc
	v_cmp_lt_u32_e32 vcc, s29, v66
	v_add_u32_e32 v66, 0x71, v191
	s_nop 0
	v_cndmask_b32_e32 v107, v176, v75, vcc
	v_cmp_lt_u32_e32 vcc, s29, v66
	v_add_u32_e32 v66, 0x52, v191
	s_nop 0
	v_cndmask_b32_e32 v91, v176, v91, vcc
	v_cmp_lt_u32_e32 vcc, s29, v66
	v_add_u32_e32 v66, 0x72, v191
	s_nop 0
	v_cndmask_b32_e32 v76, v176, v76, vcc
	v_cmp_lt_u32_e32 vcc, s29, v66
	v_add_u32_e32 v66, 0x53, v191
	s_nop 0
	v_cndmask_b32_e32 v69, v176, v92, vcc
	v_cmp_lt_u32_e32 vcc, s29, v66
	v_add_u32_e32 v66, 0x73, v191
	s_nop 0
	v_cndmask_b32_e32 v77, v176, v77, vcc
	v_cmp_lt_u32_e32 vcc, s29, v66
	v_add_u32_e32 v66, 0x58, v191
	s_nop 0
	v_cndmask_b32_e32 v70, v176, v93, vcc
	v_cmp_lt_u32_e32 vcc, s29, v66
	v_add_u32_e32 v66, 0x78, v191
	s_nop 0
	v_cndmask_b32_e32 v75, v176, v78, vcc
	v_cmp_lt_u32_e32 vcc, s29, v66
	v_add_u32_e32 v66, 0x59, v191
	s_nop 0
	v_cndmask_b32_e32 v71, v176, v94, vcc
	v_cmp_lt_u32_e32 vcc, s29, v66
	v_add_u32_e32 v66, 0x79, v191
	s_nop 0
	v_cndmask_b32_e32 v72, v176, v79, vcc
	v_cmp_lt_u32_e32 vcc, s29, v66
	s_nop 1
	v_cndmask_b32_e32 v66, v176, v95, vcc
	v_cmp_lt_u32_e32 vcc, s29, v67
	v_add_u32_e32 v67, 0x7a, v191
	s_nop 0
	v_cndmask_b32_e32 v73, v176, v80, vcc
	v_cmp_lt_u32_e32 vcc, s29, v67
	s_nop 1
	v_cndmask_b32_e32 v67, v176, v96, vcc
	v_cmp_lt_u32_e32 vcc, s29, v68
	v_add_u32_e32 v68, 0x7b, v191
	s_nop 0
	v_cndmask_b32_e32 v74, v176, v81, vcc
	v_cmp_lt_u32_e32 vcc, s29, v68
	s_nop 1
	v_cndmask_b32_e32 v68, v176, v97, vcc
	s_branch .LBB0_788
.Lmaskfast_2:
	v_mov_b32_e32 v98, v66
	v_mov_b32_e32 v99, v67
	v_mov_b32_e32 v100, v68
	v_mov_b32_e32 v101, v69
	v_mov_b32_e32 v102, v70
	v_mov_b32_e32 v103, v71
	v_mov_b32_e32 v104, v72
	v_mov_b32_e32 v105, v73
	v_mov_b32_e32 v106, v74
	v_mov_b32_e32 v107, v75
	v_mov_b32_e32 v69, v92
	v_mov_b32_e32 v70, v93
	v_mov_b32_e32 v75, v78
	v_mov_b32_e32 v71, v94
	v_mov_b32_e32 v72, v79
	v_mov_b32_e32 v66, v95
	v_mov_b32_e32 v73, v80
	v_mov_b32_e32 v67, v96
	v_mov_b32_e32 v74, v81
	v_mov_b32_e32 v68, v97

.LBB0_793:
	s_cmp_gt_i32 s42, s43
	s_cbranch_scc1 .LBB0_797
	v_sub_u32_e32 v66, v181, v190
	v_lshl_add_u32 v71, s42, 6, v66
	v_add_u32_e32 v200, 0x80, v71
	v_cmp_lt_u32_e32 vcc, 0xc5, v200
	s_cbranch_vccz .Lmaskfast_3
	v_add_u32_e32 v66, 0xffffff7f, v71
	v_cmp_lt_u32_e32 vcc, s29, v66
	s_nop 1
	v_cndmask_b32_e32 v66, v176, v34, vcc
	v_add_u32_e32 v34, 0xffffff9f, v71
	v_cmp_lt_u32_e32 vcc, s29, v34
	v_add_u32_e32 v34, 0xffffff80, v71
	s_nop 0
	v_cndmask_b32_e32 v50, v176, v50, vcc
	v_cmp_lt_u32_e32 vcc, s29, v34
	v_add_u32_e32 v34, 0xffffffa0, v71
	s_nop 0
	v_cndmask_b32_e32 v67, v176, v35, vcc
	v_cmp_lt_u32_e32 vcc, s29, v34
	v_add_u32_e32 v34, 0xffffff81, v71
	v_add_u32_e32 v35, 0xffffff9a, v71
	v_cndmask_b32_e32 v51, v176, v51, vcc
	v_cmp_lt_u32_e32 vcc, s29, v34
	v_add_u32_e32 v34, 0xffffffa1, v71
	s_nop 0
	v_cndmask_b32_e32 v68, v176, v36, vcc
	v_cmp_lt_u32_e32 vcc, s29, v34
	v_add_u32_e32 v34, 0xffffff82, v71
	s_nop 0
	v_cndmask_b32_e32 v52, v176, v52, vcc
	v_cmp_lt_u32_e32 vcc, s29, v34
	v_add_u32_e32 v34, 0xffffffa2, v71
	s_nop 0
	v_cndmask_b32_e32 v69, v176, v37, vcc
	v_cmp_lt_u32_e32 vcc, s29, v34
	v_add_u32_e32 v34, 0xffffff87, v71
	s_nop 0
	v_cndmask_b32_e32 v53, v176, v53, vcc
	v_cmp_lt_u32_e32 vcc, s29, v34
	v_add_u32_e32 v34, 0xffffffa7, v71
	s_nop 0
	v_cndmask_b32_e32 v70, v176, v38, vcc
	v_cmp_lt_u32_e32 vcc, s29, v34
	v_add_u32_e32 v34, 0xffffff88, v71
	s_nop 0
	v_cndmask_b32_e32 v38, v176, v54, vcc
	v_cmp_lt_u32_e32 vcc, s29, v34
	v_add_u32_e32 v34, 0xffffffa8, v71
	s_nop 0
	v_cndmask_b32_e32 v54, v176, v39, vcc
	v_cmp_lt_u32_e32 vcc, s29, v34
	v_add_u32_e32 v34, 0xffffff89, v71
	s_nop 0
	v_cndmask_b32_e32 v39, v176, v55, vcc
	v_cmp_lt_u32_e32 vcc, s29, v34
	v_add_u32_e32 v34, 0xffffffa9, v71
	s_nop 0
	v_cndmask_b32_e32 v55, v176, v40, vcc
	v_cmp_lt_u32_e32 vcc, s29, v34
	v_add_u32_e32 v34, 0xffffff8a, v71
	s_nop 0
	v_cndmask_b32_e32 v40, v176, v56, vcc
	v_cmp_lt_u32_e32 vcc, s29, v34
	v_add_u32_e32 v34, 0xffffffaa, v71
	s_nop 0
	v_cndmask_b32_e32 v56, v176, v41, vcc
	v_cmp_lt_u32_e32 vcc, s29, v34
	v_add_u32_e32 v34, 0xffffff8f, v71
	s_nop 0
	v_cndmask_b32_e32 v41, v176, v57, vcc
	v_cmp_lt_u32_e32 vcc, s29, v34
	v_add_u32_e32 v34, 0xffffffaf, v71
	s_nop 0
	v_cndmask_b32_e32 v57, v176, v42, vcc
	v_cmp_lt_u32_e32 vcc, s29, v34
	v_add_u32_e32 v34, 0xffffff90, v71
	s_nop 0
	v_cndmask_b32_e32 v42, v176, v58, vcc
	v_cmp_lt_u32_e32 vcc, s29, v34
	v_add_u32_e32 v34, 0xffffffb0, v71
	s_nop 0
	v_cndmask_b32_e32 v58, v176, v43, vcc
	v_cmp_lt_u32_e32 vcc, s29, v34
	v_add_u32_e32 v34, 0xffffff91, v71
	s_nop 0
	v_cndmask_b32_e32 v43, v176, v59, vcc
	v_cmp_lt_u32_e32 vcc, s29, v34
	v_add_u32_e32 v34, 0xffffffb1, v71
	s_nop 0
	v_cndmask_b32_e32 v59, v176, v44, vcc
	v_cmp_lt_u32_e32 vcc, s29, v34
	v_add_u32_e32 v34, 0xffffff92, v71
	s_nop 0
	v_cndmask_b32_e32 v44, v176, v60, vcc
	v_cmp_lt_u32_e32 vcc, s29, v34
	v_add_u32_e32 v34, 0xffffffb2, v71
	s_nop 0
	v_cndmask_b32_e32 v60, v176, v45, vcc
	v_cmp_lt_u32_e32 vcc, s29, v34
	v_add_u32_e32 v34, 0xffffff97, v71
	s_nop 0
	v_cndmask_b32_e32 v45, v176, v61, vcc
	v_cmp_lt_u32_e32 vcc, s29, v34
	v_add_u32_e32 v34, 0xffffffb7, v71
	s_nop 0
	v_cndmask_b32_e32 v61, v176, v46, vcc
	v_cmp_lt_u32_e32 vcc, s29, v34
	v_add_u32_e32 v34, 0xffffff98, v71
	s_nop 0
	v_cndmask_b32_e32 v46, v176, v62, vcc
	v_cmp_lt_u32_e32 vcc, s29, v34
	v_add_u32_e32 v34, 0xffffffb8, v71
	s_nop 0
	v_cndmask_b32_e32 v62, v176, v47, vcc
	v_cmp_lt_u32_e32 vcc, s29, v34
	v_add_u32_e32 v34, 0xffffff99, v71
	s_nop 0
	v_cndmask_b32_e32 v47, v176, v63, vcc
	v_cmp_lt_u32_e32 vcc, s29, v34
	v_add_u32_e32 v34, 0xffffffb9, v71
	s_nop 0
	v_cndmask_b32_e32 v37, v176, v48, vcc
	v_cmp_lt_u32_e32 vcc, s29, v34
	s_nop 1
	v_cndmask_b32_e32 v34, v176, v64, vcc
	v_cmp_lt_u32_e32 vcc, s29, v35
	v_add_u32_e32 v35, 0xffffffba, v71
	s_nop 0
	v_cndmask_b32_e32 v36, v176, v49, vcc
	v_cmp_lt_u32_e32 vcc, s29, v35
	s_nop 1
	v_cndmask_b32_e32 v35, v176, v65, vcc
	s_branch .Lmaskjoin_1
.Lmaskfast_3:
	v_mov_b32_e32 v66, v34
	v_mov_b32_e32 v67, v35
	v_mov_b32_e32 v68, v36
	v_mov_b32_e32 v69, v37
	v_mov_b32_e32 v70, v38
	v_mov_b32_e32 v38, v54
	v_mov_b32_e32 v54, v39
	v_mov_b32_e32 v39, v55
	v_mov_b32_e32 v55, v40
	v_mov_b32_e32 v40, v56
	v_mov_b32_e32 v56, v41
	v_mov_b32_e32 v41, v57
	v_mov_b32_e32 v57, v42
	v_mov_b32_e32 v42, v58
	v_mov_b32_e32 v58, v43
	v_mov_b32_e32 v43, v59
	v_mov_b32_e32 v59, v44
	v_mov_b32_e32 v44, v60
	v_mov_b32_e32 v60, v45
	v_mov_b32_e32 v45, v61
	v_mov_b32_e32 v61, v46
	v_mov_b32_e32 v46, v62
	v_mov_b32_e32 v62, v47
	v_mov_b32_e32 v47, v63
	v_mov_b32_e32 v37, v48
	v_mov_b32_e32 v34, v64
	v_mov_b32_e32 v36, v49
	v_mov_b32_e32 v35, v65
.Lmaskjoin_1:
.LBB0_796:
	v_exp_f32_e32 v64, v66
	v_exp_f32_e32 v66, v67
	v_exp_f32_e32 v65, v50
	v_exp_f32_e32 v67, v51
	v_exp_f32_e32 v50, v68
	v_exp_f32_e32 v68, v69
	v_exp_f32_e32 v51, v52
	v_mov_b32_e32 v48, v53
	v_exp_f32_e32 v53, v38
	v_exp_f32_e32 v69, v48
	v_exp_f32_e32 v71, v39
	v_exp_f32_e32 v52, v70
	v_mov_b32_e32 v48, v54
	v_exp_f32_e32 v54, v55
	v_exp_f32_e32 v72, v56
	v_exp_f32_e32 v55, v40
	v_exp_f32_e32 v73, v41
	v_exp_f32_e32 v56, v57
	v_exp_f32_e32 v74, v58
	v_exp_f32_e32 v57, v42
	v_exp_f32_e32 v75, v43
	v_exp_f32_e32 v58, v59
	v_exp_f32_e32 v76, v60
	v_exp_f32_e32 v59, v44
	v_exp_f32_e32 v77, v45
	v_exp_f32_e32 v60, v61
	s_bitcmp1_b32 s42, 0
	v_exp_f32_e32 v62, v62
	s_cselect_b32 s4, 0x3000, 0
	v_exp_f32_e32 v61, v46
	v_add_u32_e32 v82, s4, v183
	v_exp_f32_e32 v70, v48
	v_exp_f32_e32 v63, v47
	ds_read_b64_tr_b16 v[38:39], v82 offset:18432
	ds_read_b64_tr_b16 v[40:41], v82 offset:19968
	ds_read_b64_tr_b16 v[48:49], v82 offset:20032
	ds_read_b64_tr_b16 v[46:47], v82 offset:18496
	v_cvt_pk_bf16_f32 v42, v64, v66
	v_cvt_pk_bf16_f32 v43, v50, v68
	v_cvt_pk_bf16_f32 v44, v52, v70
	v_cvt_pk_bf16_f32 v45, v54, v72
	s_waitcnt lgkmcnt(2)
	s_nop 0
	v_mfma_f32_32x32x16_bf16 v[2:17], v[38:41], v[42:45], v[2:17]
	v_exp_f32_e32 v78, v37
	v_exp_f32_e32 v80, v36
	v_exp_f32_e32 v79, v34
	v_mov_b32_e32 v38, v35
	ds_read_b64_tr_b16 v[34:35], v82 offset:21504
	ds_read_b64_tr_b16 v[36:37], v82 offset:23040
	v_exp_f32_e32 v81, v38
	s_waitcnt lgkmcnt(2)
	v_mfma_f32_32x32x16_bf16 v[18:33], v[46:49], v[42:45], v[18:33]
	ds_read_b64_tr_b16 v[44:45], v82 offset:23104
	ds_read_b64_tr_b16 v[42:43], v82 offset:21568
	v_cvt_pk_bf16_f32 v38, v56, v74
	v_cvt_pk_bf16_f32 v39, v58, v76
	v_cvt_pk_bf16_f32 v40, v60, v62
	v_cvt_pk_bf16_f32 v41, v78, v80
	s_waitcnt lgkmcnt(2)
	s_nop 0
	v_mfma_f32_32x32x16_bf16 v[2:17], v[34:37], v[38:41], v[2:17]
	v_add_f32_e64 v34, v64, 0
	v_add_f32_e64 v35, v65, 0
	v_add_f32_e64 v36, v66, 0
	v_add_f32_e64 v37, v67, 0
	v_add_f32_e64 v34, v50, v34
	v_add_f32_e64 v35, v51, v35
	v_pk_add_f32 v[46:47], v[68:69], v[36:37]
	v_pk_add_f32 v[48:49], v[52:53], v[34:35]
	ds_read_b64_tr_b16 v[34:35], v82 offset:24576
	ds_read_b64_tr_b16 v[36:37], v82 offset:26112
	v_pk_add_f32 v[46:47], v[70:71], v[46:47]
	s_waitcnt lgkmcnt(2)
	v_mfma_f32_32x32x16_bf16 v[18:33], v[42:45], v[38:41], v[18:33]
	ds_read_b64_tr_b16 v[44:45], v82 offset:26176
	ds_read_b64_tr_b16 v[42:43], v82 offset:24640
	v_cvt_pk_bf16_f32 v38, v65, v67
	v_cvt_pk_bf16_f32 v39, v51, v69
	v_cvt_pk_bf16_f32 v40, v53, v71
	v_cvt_pk_bf16_f32 v41, v55, v73
	s_waitcnt lgkmcnt(2)
	s_nop 0
	v_mfma_f32_32x32x16_bf16 v[2:17], v[34:37], v[38:41], v[2:17]
	v_add_f32_e64 v34, v54, v48
	v_add_f32_e64 v35, v55, v49
	v_add_f32_e64 v36, v72, v46
	v_add_f32_e64 v37, v73, v47
	v_add_f32_e64 v34, v56, v34
	v_add_f32_e64 v35, v57, v35
	v_pk_add_f32 v[46:47], v[74:75], v[36:37]
	v_pk_add_f32 v[48:49], v[58:59], v[34:35]
	ds_read_b64_tr_b16 v[34:35], v82 offset:27648
	ds_read_b64_tr_b16 v[36:37], v82 offset:29184
	v_pk_add_f32 v[46:47], v[76:77], v[46:47]
	s_waitcnt lgkmcnt(2)
	v_mfma_f32_32x32x16_bf16 v[18:33], v[42:45], v[38:41], v[18:33]
	ds_read_b64_tr_b16 v[44:45], v82 offset:29248
	ds_read_b64_tr_b16 v[42:43], v82 offset:27712
	v_cvt_pk_bf16_f32 v38, v57, v75
	v_cvt_pk_bf16_f32 v39, v59, v77
	v_cvt_pk_bf16_f32 v40, v61, v63
	v_cvt_pk_bf16_f32 v41, v79, v81
	s_waitcnt lgkmcnt(0)
	s_barrier
	v_mfma_f32_32x32x16_bf16 v[2:17], v[34:37], v[38:41], v[2:17]
	v_add_f32_e64 v34, v60, v48
	v_add_f32_e64 v35, v61, v49
	v_add_f32_e64 v36, v62, v46
	v_add_f32_e64 v37, v63, v47
	v_add_f32_e64 v34, v78, v34
	v_add_f32_e64 v35, v79, v35
	v_pk_add_f32 v[36:37], v[80:81], v[36:37]
	s_nop 0
	v_pk_add_f32 v[34:35], v[34:35], v[36:37]
	v_mfma_f32_32x32x16_bf16 v[18:33], v[42:45], v[38:41], v[18:33]
	v_add_f32_e32 v34, v34, v35
	v_add_f32_e32 v0, v0, v34
